# GEMM main loop: one static s_setprio 1 for waves 4-7 at loop entry, per-phase priority flips removed
# speedup vs baseline: 1.0058x; 1.0058x over previous
; #define PG8_STAGE(bufoff, gbase, voff) do { _Pragma("unroll") for (int _i = 0; _i < 2; ++_i) \
;         __builtin_amdgcn_global_load_lds((const unsigned*)((const char*)(gbase) + (voff)[_i]), (LAS unsigned*)(lds + (bufoff) + ldsw + _i * 8192), 16, 0, 0); } while (0)
; #define PG8_LDA(dst, b, h) do { _Pragma("unroll") for (int m = 0; m < 4; ++m) _Pragma("unroll") for (int k = 0; k < 2; ++k) dst[m][k] = *(const LAS h16x8*)(lds + PG8_SA(b, h) + aoff + m * 2048 + k * 1024); } while (0)
; #define PG8_LDB(dst, b, h) do { _Pragma("unroll") for (int n = 0; n < 2; ++n) _Pragma("unroll") for (int k = 0; k < 2; ++k) dst[n][k] = *(const LAS h16x8*)(lds + PG8_SB(b, h) + boff + n * 2048 + k * 1024); } while (0)
; #define PG8_MMA(ai, bj, At, Bt) do { __builtin_amdgcn_s_setprio(1); _Pragma("unroll") for (int m = 0; m < 4; ++m) _Pragma("unroll") for (int n = 0; n < 2; ++n) _Pragma("unroll") for (int k = 0; k < 2; ++k) \
;         acc[ai][bj][m][n] = __builtin_amdgcn_mfma_f32_16x16x32_f16(Bt[n][k], At[m][k], acc[ai][bj][m][n], 0, 0, 0); __builtin_amdgcn_s_setprio(0); } while (0)
; #define PG8_WAIT_L(n) asm volatile("s_waitcnt lgkmcnt(" #n ")" ::: "memory")
; #define PG8_BAR __builtin_amdgcn_s_barrier()
; #define PG8_SCHED __builtin_amdgcn_sched_barrier(0)
; __device__ __forceinline__ void gemm_phase(LAS unsigned char* lds, const Gemm g, const StaticOrder& S, const Epi& E) {
;     ...
;         for (int t = 0; t < nt; t += 2) {
;             const bool last = (t == nt - 2);
;             const char* a1 = cA + PG8_KOFF(t + 1);
;             const char* a2 = last ? nA : cA + PG8_KOFF(t + 2); const char* b2 = last ? nB : cB + (size_t)(t + 2) * kstep;
;             const char* a3 = a2 + kstep; const char* b3 = b2 + kstep;
;             PG8_LDB(B0, 0, 0); PG8_SCHED; PG8_LDA(At, 0, 0); PG8_STAGE(PG8_SA(1, 1), a1 + hstepA, voffA);
;             PG8_WAIT_L(8); PG8_BAR; PG8_WAIT_L(0); PG8_MMA(0, 0, At, B0); PG8_BAR; PG8_SCHED;
;     ...
; #pragma unroll
;         for (int a = 0; a < 2; ++a)
; #pragma unroll
;             for (int b = 0; b < 2; ++b)
; #pragma unroll
;                 for (int m = 0; m < 4; ++m)
; #pragma unroll
;                     for (int n = 0; n < 2; ++n) acc[a][b][m][n] = (f32x4){0.f, 0.f, 0.f, 0.f};
;         cur = nxt; cA = nA; cB = nB; ++ui;
.LBB0_761:
	s_add_u32 s0, s34, 0x80
	s_addc_u32 s1, s35, 0
	s_add_u32 s27, s36, 0x100
	v_mov_b32_e32 v0, 0
	s_addc_u32 s33, s37, 0
	s_mov_b32 s34, 0
	v_mov_b32_e32 v1, v0
	v_mov_b32_e32 v2, v0
	v_mov_b32_e32 v3, v0
	v_mov_b32_e32 v4, v0
	v_mov_b32_e32 v5, v0
	v_mov_b32_e32 v6, v0
	v_mov_b32_e32 v7, v0
	v_mov_b32_e32 v16, v0
	v_mov_b32_e32 v17, v0
	v_mov_b32_e32 v18, v0
	v_mov_b32_e32 v19, v0
	s_waitcnt vmcnt(0)
	v_mov_b32_e32 v20, v0
	v_mov_b32_e32 v21, v0
	v_mov_b32_e32 v22, v0
	v_mov_b32_e32 v23, v0
	v_mov_b32_e32 v32, v0
	v_mov_b32_e32 v33, v0
	v_mov_b32_e32 v34, v0
	v_mov_b32_e32 v35, v0
	v_mov_b32_e32 v36, v0
	v_mov_b32_e32 v37, v0
	v_mov_b32_e32 v38, v0
	v_mov_b32_e32 v39, v0
	v_mov_b32_e32 v48, v0
	v_mov_b32_e32 v49, v0
	v_mov_b32_e32 v50, v0
	v_mov_b32_e32 v51, v0
	v_mov_b32_e32 v52, v0
	v_mov_b32_e32 v53, v0
	v_mov_b32_e32 v54, v0
	v_mov_b32_e32 v55, v0
	v_mov_b32_e32 v8, v0
	v_mov_b32_e32 v9, v0
	v_mov_b32_e32 v10, v0
	v_mov_b32_e32 v11, v0
	v_mov_b32_e32 v12, v0
	v_mov_b32_e32 v13, v0
	v_mov_b32_e32 v14, v0
	v_mov_b32_e32 v15, v0
	v_mov_b32_e32 v24, v0
	v_mov_b32_e32 v25, v0
	v_mov_b32_e32 v26, v0
	v_mov_b32_e32 v27, v0
	v_mov_b32_e32 v28, v0
	v_mov_b32_e32 v29, v0
	v_mov_b32_e32 v30, v0
	v_mov_b32_e32 v31, v0
	v_mov_b32_e32 v40, v0
	v_mov_b32_e32 v41, v0
	v_mov_b32_e32 v42, v0
	v_mov_b32_e32 v43, v0
	v_mov_b32_e32 v44, v0
	v_mov_b32_e32 v45, v0
	v_mov_b32_e32 v46, v0
	v_mov_b32_e32 v47, v0
	v_mov_b32_e32 v56, v0
	v_mov_b32_e32 v57, v0
	v_mov_b32_e32 v58, v0
	v_mov_b32_e32 v59, v0
	v_mov_b32_e32 v60, v0
	v_mov_b32_e32 v61, v0
	v_mov_b32_e32 v62, v0
	v_mov_b32_e32 v63, v0
	v_mov_b32_e32 v64, v0
	v_mov_b32_e32 v65, v0
	v_mov_b32_e32 v66, v0
	v_mov_b32_e32 v67, v0
	v_mov_b32_e32 v68, v0
	v_mov_b32_e32 v69, v0
	v_mov_b32_e32 v70, v0
	v_mov_b32_e32 v71, v0
	v_mov_b32_e32 v80, v0
	v_mov_b32_e32 v81, v0
	v_mov_b32_e32 v82, v0
	v_mov_b32_e32 v83, v0
	v_mov_b32_e32 v84, v0
	v_mov_b32_e32 v85, v0
	v_mov_b32_e32 v86, v0
	v_mov_b32_e32 v87, v0
	v_mov_b32_e32 v96, v0
	v_mov_b32_e32 v97, v0
	v_mov_b32_e32 v98, v0
	v_mov_b32_e32 v99, v0
	v_mov_b32_e32 v100, v0
	v_mov_b32_e32 v101, v0
	v_mov_b32_e32 v102, v0
	v_mov_b32_e32 v103, v0
	v_mov_b32_e32 v112, v0
	v_mov_b32_e32 v113, v0
	v_mov_b32_e32 v114, v0
	v_mov_b32_e32 v115, v0
	v_mov_b32_e32 v116, v0
	v_mov_b32_e32 v117, v0
	v_mov_b32_e32 v118, v0
	v_mov_b32_e32 v119, v0
	v_mov_b32_e32 v72, v0
	v_mov_b32_e32 v73, v0
	v_mov_b32_e32 v74, v0
	v_mov_b32_e32 v75, v0
	v_mov_b32_e32 v76, v0
	v_mov_b32_e32 v77, v0
	v_mov_b32_e32 v78, v0
	v_mov_b32_e32 v79, v0
	v_mov_b32_e32 v88, v0
	v_mov_b32_e32 v89, v0
	v_mov_b32_e32 v90, v0
	v_mov_b32_e32 v91, v0
	v_mov_b32_e32 v92, v0
	v_mov_b32_e32 v93, v0
	v_mov_b32_e32 v94, v0
	v_mov_b32_e32 v95, v0
	v_mov_b32_e32 v104, v0
	v_mov_b32_e32 v105, v0
	v_mov_b32_e32 v106, v0
	v_mov_b32_e32 v107, v0
	v_mov_b32_e32 v108, v0
	v_mov_b32_e32 v109, v0
	v_mov_b32_e32 v110, v0
	v_mov_b32_e32 v111, v0
	v_mov_b32_e32 v120, v0
	v_mov_b32_e32 v121, v0
	v_mov_b32_e32 v122, v0
	v_mov_b32_e32 v123, v0
	v_mov_b32_e32 v124, v0
	v_mov_b32_e32 v125, v0
	v_mov_b32_e32 v126, v0
	v_mov_b32_e32 v127, v0
	s_cmpk_gt_u32 s57, 0xff
	s_cbranch_scc0 .Lprio_skip
	s_setprio 1
.Lprio_skip:
.LBB0_762:
	s_cmp_gt_u32 s34, 15
	s_cselect_b64 s[36:37], -1, 0
	s_and_b64 s[36:37], s[6:7], s[36:37]
	s_and_b64 s[36:37], s[36:37], exec
	s_cselect_b32 s42, 0xfffff000, 0
	s_cselect_b32 s43, -1, 0
	s_add_i32 s38, s34, 2
	s_cmp_gt_u32 s34, 13
	s_cselect_b64 s[36:37], -1, 0
	s_and_b64 s[36:37], s[6:7], s[36:37]
	s_and_b64 s[36:37], s[36:37], exec
	s_cselect_b32 s36, 0xfffff000, 0
	s_cselect_b32 s35, -1, 0
	s_add_u32 s36, s0, s36
	s_addc_u32 s35, s1, s35
	s_add_u32 s36, s36, 0x80
	s_addc_u32 s35, s35, 0
	s_add_i32 s39, 0, 0x10000
	v_add_u32_e32 v140, s39, v238
	ds_read_b128 v[128:131], v140
	ds_read_b128 v[132:135], v140 offset:1024
	ds_read_b128 v[136:139], v140 offset:2048
	ds_read_b128 v[140:143], v140 offset:3072
	s_cmp_eq_u32 s66, s34
	s_cselect_b32 s34, s4, s36
	s_cselect_b32 s35, s5, s35
	s_cselect_b32 s37, s29, s33
	s_cselect_b32 s36, s28, s27
	v_lshl_add_u64 v[176:177], s[0:1], 0, v[212:213]
	v_lshl_add_u64 v[176:177], v[176:177], 0, s[42:43]
	s_add_i32 m0, s58, 0xc000
	ds_read_b128 v[144:147], v239
	ds_read_b128 v[148:151], v239 offset:1024
	ds_read_b128 v[152:155], v239 offset:2048
	ds_read_b128 v[156:159], v239 offset:3072
	ds_read_b128 v[160:163], v239 offset:4096
	ds_read_b128 v[164:167], v239 offset:5120
	ds_read_b128 v[168:171], v239 offset:6144
	ds_read_b128 v[172:175], v239 offset:7168
	global_load_lds_dwordx4 v[176:177], off
	v_lshl_add_u64 v[176:177], s[0:1], 0, v[214:215]
	v_lshl_add_u64 v[176:177], v[176:177], 0, s[42:43]
	s_add_i32 m0, s58, 0xe000
	s_nop 0
	global_load_lds_dwordx4 v[176:177], off
	s_waitcnt lgkmcnt(8)
	s_barrier
	s_waitcnt lgkmcnt(0)
	s_waitcnt lgkmcnt(0)
	v_mfma_f32_16x16x32_f16 v[124:127], v[128:131], v[144:147], v[124:127]
	v_mfma_f32_16x16x32_f16 v[120:123], v[136:139], v[144:147], v[120:123]
	v_mfma_f32_16x16x32_f16 v[108:111], v[128:131], v[152:155], v[108:111]
	v_mfma_f32_16x16x32_f16 v[104:107], v[136:139], v[152:155], v[104:107]
	v_mfma_f32_16x16x32_f16 v[92:95], v[128:131], v[160:163], v[92:95]
	v_mfma_f32_16x16x32_f16 v[88:91], v[136:139], v[160:163], v[88:91]
	v_mfma_f32_16x16x32_f16 v[76:79], v[128:131], v[168:171], v[76:79]
	v_mfma_f32_16x16x32_f16 v[72:75], v[136:139], v[168:171], v[72:75]
	v_mfma_f32_16x16x32_f16 v[124:127], v[132:135], v[148:151], v[124:127]
	v_mfma_f32_16x16x32_f16 v[120:123], v[140:143], v[148:151], v[120:123]
	v_mfma_f32_16x16x32_f16 v[108:111], v[132:135], v[156:159], v[108:111]
	v_mfma_f32_16x16x32_f16 v[104:107], v[140:143], v[156:159], v[104:107]
	v_mfma_f32_16x16x32_f16 v[92:95], v[132:135], v[164:167], v[92:95]
	v_mfma_f32_16x16x32_f16 v[88:91], v[140:143], v[164:167], v[88:91]
	v_mfma_f32_16x16x32_f16 v[76:79], v[132:135], v[172:175], v[76:79]
	v_mfma_f32_16x16x32_f16 v[72:75], v[140:143], v[172:175], v[72:75]
	s_barrier
; #define PG8_STAGE(bufoff, gbase, voff) do { _Pragma("unroll") for (int _i = 0; _i < 2; ++_i) \
;         __builtin_amdgcn_global_load_lds((const unsigned*)((const char*)(gbase) + (voff)[_i]), (LAS unsigned*)(lds + (bufoff) + ldsw + _i * 8192), 16, 0, 0); } while (0)
; #define PG8_LDA(dst, b, h) do { _Pragma("unroll") for (int m = 0; m < 4; ++m) _Pragma("unroll") for (int k = 0; k < 2; ++k) dst[m][k] = *(const LAS h16x8*)(lds + PG8_SA(b, h) + aoff + m * 2048 + k * 1024); } while (0)
; #define PG8_LDB(dst, b, h) do { _Pragma("unroll") for (int n = 0; n < 2; ++n) _Pragma("unroll") for (int k = 0; k < 2; ++k) dst[n][k] = *(const LAS h16x8*)(lds + PG8_SB(b, h) + boff + n * 2048 + k * 1024); } while (0)
; #define PG8_MMA(ai, bj, At, Bt) do { __builtin_amdgcn_s_setprio(1); _Pragma("unroll") for (int m = 0; m < 4; ++m) _Pragma("unroll") for (int n = 0; n < 2; ++n) _Pragma("unroll") for (int k = 0; k < 2; ++k) \
;         acc[ai][bj][m][n] = __builtin_amdgcn_mfma_f32_16x16x32_f16(Bt[n][k], At[m][k], acc[ai][bj][m][n], 0, 0, 0); __builtin_amdgcn_s_setprio(0); } while (0)
; #define PG8_WAIT_V(n) asm volatile("s_waitcnt vmcnt(" #n ")" ::: "memory")
; #define PG8_WAIT_L(n) asm volatile("s_waitcnt lgkmcnt(" #n ")" ::: "memory")
; #define PG8_BAR __builtin_amdgcn_s_barrier()
; #define PG8_SCHED __builtin_amdgcn_sched_barrier(0)
; __device__ __forceinline__ void gemm_phase(LAS unsigned char* lds, const Gemm g, const StaticOrder& S, const Epi& E) {
;     ...
;             PG8_LDB(B1, 0, 1); PG8_STAGE(PG8_SB(0, 0), b2, voffB);
;             PG8_BAR; PG8_WAIT_L(0); PG8_MMA(0, 1, At, B1); PG8_BAR;
;             PG8_LDA(At, 0, 1); PG8_STAGE(PG8_SA(0, 0), a2, voffA);
;             PG8_BAR; PG8_WAIT_L(0); PG8_MMA(1, 0, At, B0); PG8_BAR; PG8_SCHED;
;             PG8_STAGE(PG8_SB(0, 1), b2 + hstepB, voffB);
;             PG8_WAIT_V(6); PG8_BAR; PG8_MMA(1, 1, At, B1); PG8_BAR;
;             PG8_LDB(B0, 1, 0); PG8_SCHED; PG8_LDA(At, 1, 0); PG8_STAGE(PG8_SA(0, 1), a2 + hstepA, voffA);
;             PG8_WAIT_L(8); PG8_BAR; PG8_WAIT_L(0); PG8_MMA(0, 0, At, B0); PG8_BAR; PG8_SCHED;
;             PG8_LDB(B1, 1, 1); PG8_STAGE(PG8_SB(1, 0), b3, voffB);
;             PG8_BAR; PG8_WAIT_L(0); PG8_MMA(0, 1, At, B1); PG8_BAR;
;             PG8_LDA(At, 1, 1); PG8_STAGE(PG8_SA(1, 0), a3, voffA);
	s_add_i32 s42, 0, 0x14000
	s_add_i32 s39, s39, s31
	v_add_u32_e32 v188, s42, v238
	v_lshl_add_u64 v[192:193], s[36:37], 0, v[206:207]
	s_mov_b32 m0, s39
	ds_read_b128 v[176:179], v188
	ds_read_b128 v[180:183], v188 offset:1024
	ds_read_b128 v[184:187], v188 offset:2048
	ds_read_b128 v[188:191], v188 offset:3072
	global_load_lds_dwordx4 v[192:193], off
	v_lshl_add_u64 v[194:195], s[36:37], 0, v[210:211]
	s_add_i32 m0, s39, 0x2000
	s_nop 0
	global_load_lds_dwordx4 v[194:195], off
	s_barrier
	s_waitcnt lgkmcnt(0)
	s_waitcnt lgkmcnt(0)
	v_mfma_f32_16x16x32_f16 v[116:119], v[176:179], v[144:147], v[116:119]
	v_mfma_f32_16x16x32_f16 v[112:115], v[184:187], v[144:147], v[112:115]
	v_mfma_f32_16x16x32_f16 v[100:103], v[176:179], v[152:155], v[100:103]
	v_mfma_f32_16x16x32_f16 v[96:99], v[184:187], v[152:155], v[96:99]
	v_mfma_f32_16x16x32_f16 v[84:87], v[176:179], v[160:163], v[84:87]
	v_mfma_f32_16x16x32_f16 v[80:83], v[184:187], v[160:163], v[80:83]
	v_mfma_f32_16x16x32_f16 v[68:71], v[176:179], v[168:171], v[68:71]
	v_mfma_f32_16x16x32_f16 v[64:67], v[184:187], v[168:171], v[64:67]
	v_mfma_f32_16x16x32_f16 v[116:119], v[180:183], v[148:151], v[116:119]
	v_mfma_f32_16x16x32_f16 v[112:115], v[188:191], v[148:151], v[112:115]
	v_mfma_f32_16x16x32_f16 v[100:103], v[180:183], v[156:159], v[100:103]
	v_mfma_f32_16x16x32_f16 v[96:99], v[188:191], v[156:159], v[96:99]
	v_mfma_f32_16x16x32_f16 v[84:87], v[180:183], v[164:167], v[84:87]
	v_mfma_f32_16x16x32_f16 v[80:83], v[188:191], v[164:167], v[80:83]
	v_mfma_f32_16x16x32_f16 v[68:71], v[180:183], v[172:175], v[68:71]
	v_mfma_f32_16x16x32_f16 v[64:67], v[188:191], v[172:175], v[64:67]
	s_mov_b32 m0, s58
	v_lshl_add_u64 v[216:217], s[34:35], 0, v[204:205]
	s_barrier
	ds_read_b128 v[144:147], v239 offset:16384
	ds_read_b128 v[148:151], v239 offset:17408
	ds_read_b128 v[152:155], v239 offset:18432
	ds_read_b128 v[156:159], v239 offset:19456
	ds_read_b128 v[160:163], v239 offset:20480
	ds_read_b128 v[164:167], v239 offset:21504
	ds_read_b128 v[168:171], v239 offset:22528
	ds_read_b128 v[172:175], v239 offset:23552
	global_load_lds_dwordx4 v[216:217], off
	v_lshl_add_u64 v[218:219], s[34:35], 0, v[208:209]
	s_mov_b32 m0, s59
	s_nop 0
	global_load_lds_dwordx4 v[218:219], off
	s_barrier
	s_waitcnt lgkmcnt(0)
	s_waitcnt lgkmcnt(0)
	v_mfma_f32_16x16x32_f16 v[60:63], v[128:131], v[144:147], v[60:63]
	v_mfma_f32_16x16x32_f16 v[56:59], v[136:139], v[144:147], v[56:59]
	v_mfma_f32_16x16x32_f16 v[44:47], v[128:131], v[152:155], v[44:47]
	v_mfma_f32_16x16x32_f16 v[40:43], v[136:139], v[152:155], v[40:43]
	v_mfma_f32_16x16x32_f16 v[28:31], v[128:131], v[160:163], v[28:31]
	v_mfma_f32_16x16x32_f16 v[24:27], v[136:139], v[160:163], v[24:27]
	v_mfma_f32_16x16x32_f16 v[12:15], v[128:131], v[168:171], v[12:15]
	v_mfma_f32_16x16x32_f16 v[8:11], v[136:139], v[168:171], v[8:11]
	v_mfma_f32_16x16x32_f16 v[60:63], v[132:135], v[148:151], v[60:63]
	v_mfma_f32_16x16x32_f16 v[56:59], v[140:143], v[148:151], v[56:59]
	v_mfma_f32_16x16x32_f16 v[44:47], v[132:135], v[156:159], v[44:47]
	v_mfma_f32_16x16x32_f16 v[40:43], v[140:143], v[156:159], v[40:43]
	v_mfma_f32_16x16x32_f16 v[28:31], v[132:135], v[164:167], v[28:31]
	v_mfma_f32_16x16x32_f16 v[24:27], v[140:143], v[164:167], v[24:27]
	v_mfma_f32_16x16x32_f16 v[12:15], v[132:135], v[172:175], v[12:15]
	v_mfma_f32_16x16x32_f16 v[8:11], v[140:143], v[172:175], v[8:11]
	s_barrier
	s_add_u32 s36, s36, s18
	s_addc_u32 s37, s37, s19
	s_add_i32 s39, s42, s31
	v_lshl_add_u64 v[220:221], s[36:37], 0, v[206:207]
	s_mov_b32 m0, s39
	v_lshl_add_u64 v[222:223], s[36:37], 0, v[210:211]
	global_load_lds_dwordx4 v[220:221], off
	s_add_i32 m0, s39, 0x2000
	s_nop 0
	global_load_lds_dwordx4 v[222:223], off
	s_waitcnt vmcnt(6)
	s_barrier
	v_mfma_f32_16x16x32_f16 v[52:55], v[176:179], v[144:147], v[52:55]
	v_mfma_f32_16x16x32_f16 v[48:51], v[184:187], v[144:147], v[48:51]
	v_mfma_f32_16x16x32_f16 v[36:39], v[176:179], v[152:155], v[36:39]
	v_mfma_f32_16x16x32_f16 v[32:35], v[184:187], v[152:155], v[32:35]
	v_mfma_f32_16x16x32_f16 v[20:23], v[176:179], v[160:163], v[20:23]
	v_mfma_f32_16x16x32_f16 v[16:19], v[184:187], v[160:163], v[16:19]
	v_mfma_f32_16x16x32_f16 v[4:7], v[176:179], v[168:171], v[4:7]
	v_mfma_f32_16x16x32_f16 v[0:3], v[184:187], v[168:171], v[0:3]
	v_mfma_f32_16x16x32_f16 v[52:55], v[180:183], v[148:151], v[52:55]
	v_mfma_f32_16x16x32_f16 v[48:51], v[188:191], v[148:151], v[48:51]
	v_mfma_f32_16x16x32_f16 v[36:39], v[180:183], v[156:159], v[36:39]
	v_mfma_f32_16x16x32_f16 v[32:35], v[188:191], v[156:159], v[32:35]
	v_mfma_f32_16x16x32_f16 v[20:23], v[180:183], v[164:167], v[20:23]
	v_mfma_f32_16x16x32_f16 v[16:19], v[188:191], v[164:167], v[16:19]
	v_mfma_f32_16x16x32_f16 v[4:7], v[180:183], v[172:175], v[4:7]
	v_mfma_f32_16x16x32_f16 v[0:3], v[188:191], v[172:175], v[0:3]
	s_add_i32 s36, 0, 0x18000
	v_add_u32_e32 v140, s36, v238
	s_barrier
	ds_read_b128 v[128:131], v140
	ds_read_b128 v[132:135], v140 offset:1024
	ds_read_b128 v[136:139], v140 offset:2048
	ds_read_b128 v[140:143], v140 offset:3072
	s_add_u32 s34, s34, s16
	s_addc_u32 s35, s35, s17
	s_mov_b32 m0, s60
	v_lshl_add_u64 v[176:177], s[34:35], 0, v[204:205]
	ds_read_b128 v[144:147], v239 offset:32768
	ds_read_b128 v[148:151], v239 offset:33792
	ds_read_b128 v[152:155], v239 offset:34816
	ds_read_b128 v[156:159], v239 offset:35840
	ds_read_b128 v[160:163], v239 offset:36864
	ds_read_b128 v[164:167], v239 offset:37888
	ds_read_b128 v[168:171], v239 offset:38912
	ds_read_b128 v[172:175], v239 offset:39936
	global_load_lds_dwordx4 v[176:177], off
	v_lshl_add_u64 v[176:177], s[34:35], 0, v[208:209]
	s_mov_b32 m0, s61
	s_nop 0
	global_load_lds_dwordx4 v[176:177], off
	s_waitcnt lgkmcnt(8)
	s_barrier
; #define PG8_STAGE(bufoff, gbase, voff) do { _Pragma("unroll") for (int _i = 0; _i < 2; ++_i) \
;         __builtin_amdgcn_global_load_lds((const unsigned*)((const char*)(gbase) + (voff)[_i]), (LAS unsigned*)(lds + (bufoff) + ldsw + _i * 8192), 16, 0, 0); } while (0)
; #define PG8_LDA(dst, b, h) do { _Pragma("unroll") for (int m = 0; m < 4; ++m) _Pragma("unroll") for (int k = 0; k < 2; ++k) dst[m][k] = *(const LAS h16x8*)(lds + PG8_SA(b, h) + aoff + m * 2048 + k * 1024); } while (0)
; #define PG8_LDB(dst, b, h) do { _Pragma("unroll") for (int n = 0; n < 2; ++n) _Pragma("unroll") for (int k = 0; k < 2; ++k) dst[n][k] = *(const LAS h16x8*)(lds + PG8_SB(b, h) + boff + n * 2048 + k * 1024); } while (0)
; #define PG8_MMA(ai, bj, At, Bt) do { __builtin_amdgcn_s_setprio(1); _Pragma("unroll") for (int m = 0; m < 4; ++m) _Pragma("unroll") for (int n = 0; n < 2; ++n) _Pragma("unroll") for (int k = 0; k < 2; ++k) \
;         acc[ai][bj][m][n] = __builtin_amdgcn_mfma_f32_16x16x32_f16(Bt[n][k], At[m][k], acc[ai][bj][m][n], 0, 0, 0); __builtin_amdgcn_s_setprio(0); } while (0)
; #define PG8_WAIT_V(n) asm volatile("s_waitcnt vmcnt(" #n ")" ::: "memory")
; #define PG8_WAIT_L(n) asm volatile("s_waitcnt lgkmcnt(" #n ")" ::: "memory")
; #define PG8_BAR __builtin_amdgcn_s_barrier()
; #define PG8_SCHED __builtin_amdgcn_sched_barrier(0)
; __device__ __forceinline__ void gemm_phase(LAS unsigned char* lds, const Gemm g, const StaticOrder& S, const Epi& E) {
;     ...
;             PG8_WAIT_L(8); PG8_BAR; PG8_WAIT_L(0); PG8_MMA(0, 0, At, B0); PG8_BAR; PG8_SCHED;
;             PG8_LDB(B1, 1, 1); PG8_STAGE(PG8_SB(1, 0), b3, voffB);
;             PG8_BAR; PG8_WAIT_L(0); PG8_MMA(0, 1, At, B1); PG8_BAR;
;             PG8_LDA(At, 1, 1); PG8_STAGE(PG8_SA(1, 0), a3, voffA);
;             PG8_BAR; PG8_WAIT_L(0); PG8_MMA(1, 0, At, B0); PG8_BAR; PG8_SCHED;
;             PG8_STAGE(PG8_SB(1, 1), b3 + hstepB, voffB);
;             PG8_WAIT_V(6); PG8_BAR; PG8_MMA(1, 1, At, B1); PG8_BAR;
;         }
;         E(acc, cur, wr, wc, fr, fq);
;         if (!has_next) break;
	s_waitcnt lgkmcnt(0)
	s_waitcnt lgkmcnt(0)
	v_mfma_f32_16x16x32_f16 v[124:127], v[128:131], v[144:147], v[124:127]
	v_mfma_f32_16x16x32_f16 v[120:123], v[136:139], v[144:147], v[120:123]
	v_mfma_f32_16x16x32_f16 v[108:111], v[128:131], v[152:155], v[108:111]
	v_mfma_f32_16x16x32_f16 v[104:107], v[136:139], v[152:155], v[104:107]
	v_mfma_f32_16x16x32_f16 v[92:95], v[128:131], v[160:163], v[92:95]
	v_mfma_f32_16x16x32_f16 v[88:91], v[136:139], v[160:163], v[88:91]
	v_mfma_f32_16x16x32_f16 v[76:79], v[128:131], v[168:171], v[76:79]
	v_mfma_f32_16x16x32_f16 v[72:75], v[136:139], v[168:171], v[72:75]
	v_mfma_f32_16x16x32_f16 v[124:127], v[132:135], v[148:151], v[124:127]
	v_mfma_f32_16x16x32_f16 v[120:123], v[140:143], v[148:151], v[120:123]
	v_mfma_f32_16x16x32_f16 v[108:111], v[132:135], v[156:159], v[108:111]
	v_mfma_f32_16x16x32_f16 v[104:107], v[140:143], v[156:159], v[104:107]
	v_mfma_f32_16x16x32_f16 v[92:95], v[132:135], v[164:167], v[92:95]
	v_mfma_f32_16x16x32_f16 v[88:91], v[140:143], v[164:167], v[88:91]
	v_mfma_f32_16x16x32_f16 v[76:79], v[132:135], v[172:175], v[76:79]
	v_mfma_f32_16x16x32_f16 v[72:75], v[140:143], v[172:175], v[72:75]
	s_barrier
	s_add_i32 s34, 0, 0x1c000
	s_add_i32 s35, s36, s31
	v_add_u32_e32 v188, s34, v238
	v_lshl_add_u64 v[192:193], v[192:193], 0, s[80:81]
	s_mov_b32 m0, s35
	ds_read_b128 v[176:179], v188
	ds_read_b128 v[180:183], v188 offset:1024
	ds_read_b128 v[184:187], v188 offset:2048
	ds_read_b128 v[188:191], v188 offset:3072
	global_load_lds_dwordx4 v[192:193], off
	v_lshl_add_u64 v[192:193], v[194:195], 0, s[80:81]
	s_add_i32 m0, s35, 0x2000
	s_nop 0
	global_load_lds_dwordx4 v[192:193], off
	s_barrier
	s_waitcnt lgkmcnt(0)
	s_waitcnt lgkmcnt(0)
	v_mfma_f32_16x16x32_f16 v[116:119], v[176:179], v[144:147], v[116:119]
	v_mfma_f32_16x16x32_f16 v[112:115], v[184:187], v[144:147], v[112:115]
	v_mfma_f32_16x16x32_f16 v[100:103], v[176:179], v[152:155], v[100:103]
	v_mfma_f32_16x16x32_f16 v[96:99], v[184:187], v[152:155], v[96:99]
	v_mfma_f32_16x16x32_f16 v[84:87], v[176:179], v[160:163], v[84:87]
	v_mfma_f32_16x16x32_f16 v[80:83], v[184:187], v[160:163], v[80:83]
	v_mfma_f32_16x16x32_f16 v[68:71], v[176:179], v[168:171], v[68:71]
	v_mfma_f32_16x16x32_f16 v[64:67], v[184:187], v[168:171], v[64:67]
	v_mfma_f32_16x16x32_f16 v[116:119], v[180:183], v[148:151], v[116:119]
	v_mfma_f32_16x16x32_f16 v[112:115], v[188:191], v[148:151], v[112:115]
	v_mfma_f32_16x16x32_f16 v[100:103], v[180:183], v[156:159], v[100:103]
	v_mfma_f32_16x16x32_f16 v[96:99], v[188:191], v[156:159], v[96:99]
	v_mfma_f32_16x16x32_f16 v[84:87], v[180:183], v[164:167], v[84:87]
	v_mfma_f32_16x16x32_f16 v[80:83], v[188:191], v[164:167], v[80:83]
	v_mfma_f32_16x16x32_f16 v[68:71], v[180:183], v[172:175], v[68:71]
	v_mfma_f32_16x16x32_f16 v[64:67], v[188:191], v[172:175], v[64:67]
	s_mov_b32 m0, s62
	v_lshl_add_u64 v[192:193], v[216:217], 0, s[80:81]
	s_barrier
	ds_read_b128 v[144:147], v239 offset:49152
	ds_read_b128 v[148:151], v239 offset:50176
	ds_read_b128 v[152:155], v239 offset:51200
	ds_read_b128 v[156:159], v239 offset:52224
	ds_read_b128 v[160:163], v239 offset:53248
	ds_read_b128 v[164:167], v239 offset:54272
	ds_read_b128 v[168:171], v239 offset:55296
	ds_read_b128 v[172:175], v239 offset:56320
	global_load_lds_dwordx4 v[192:193], off
	v_lshl_add_u64 v[192:193], v[218:219], 0, s[80:81]
	s_mov_b32 m0, s63
	s_nop 0
	global_load_lds_dwordx4 v[192:193], off
	s_barrier
	s_waitcnt lgkmcnt(0)
	s_waitcnt lgkmcnt(0)
	v_mfma_f32_16x16x32_f16 v[60:63], v[128:131], v[144:147], v[60:63]
	v_mfma_f32_16x16x32_f16 v[56:59], v[136:139], v[144:147], v[56:59]
	v_mfma_f32_16x16x32_f16 v[44:47], v[128:131], v[152:155], v[44:47]
	v_mfma_f32_16x16x32_f16 v[40:43], v[136:139], v[152:155], v[40:43]
	v_mfma_f32_16x16x32_f16 v[28:31], v[128:131], v[160:163], v[28:31]
	v_mfma_f32_16x16x32_f16 v[24:27], v[136:139], v[160:163], v[24:27]
	v_mfma_f32_16x16x32_f16 v[12:15], v[128:131], v[168:171], v[12:15]
	v_mfma_f32_16x16x32_f16 v[8:11], v[136:139], v[168:171], v[8:11]
	v_mfma_f32_16x16x32_f16 v[60:63], v[132:135], v[148:151], v[60:63]
	v_mfma_f32_16x16x32_f16 v[56:59], v[140:143], v[148:151], v[56:59]
	v_mfma_f32_16x16x32_f16 v[44:47], v[132:135], v[156:159], v[44:47]
	v_mfma_f32_16x16x32_f16 v[40:43], v[140:143], v[156:159], v[40:43]
	v_mfma_f32_16x16x32_f16 v[28:31], v[132:135], v[164:167], v[28:31]
	v_mfma_f32_16x16x32_f16 v[24:27], v[140:143], v[164:167], v[24:27]
	v_mfma_f32_16x16x32_f16 v[12:15], v[132:135], v[172:175], v[12:15]
	v_mfma_f32_16x16x32_f16 v[8:11], v[140:143], v[172:175], v[8:11]
	s_barrier
	s_add_i32 s34, s34, s31
	v_lshl_add_u64 v[128:129], v[220:221], 0, s[80:81]
	s_mov_b32 m0, s34
	s_nop 0
	global_load_lds_dwordx4 v[128:129], off
	v_lshl_add_u64 v[128:129], v[222:223], 0, s[80:81]
	s_add_i32 m0, s34, 0x2000
	s_nop 0
	global_load_lds_dwordx4 v[128:129], off
	s_waitcnt vmcnt(6)
	s_barrier
	v_mfma_f32_16x16x32_f16 v[52:55], v[176:179], v[144:147], v[52:55]
	v_mfma_f32_16x16x32_f16 v[48:51], v[184:187], v[144:147], v[48:51]
	v_mfma_f32_16x16x32_f16 v[36:39], v[176:179], v[152:155], v[36:39]
	v_mfma_f32_16x16x32_f16 v[32:35], v[184:187], v[152:155], v[32:35]
	v_mfma_f32_16x16x32_f16 v[20:23], v[176:179], v[160:163], v[20:23]
	v_mfma_f32_16x16x32_f16 v[16:19], v[184:187], v[160:163], v[16:19]
	v_mfma_f32_16x16x32_f16 v[4:7], v[176:179], v[168:171], v[4:7]
	v_mfma_f32_16x16x32_f16 v[0:3], v[184:187], v[168:171], v[0:3]
	v_mfma_f32_16x16x32_f16 v[52:55], v[180:183], v[148:151], v[52:55]
	v_mfma_f32_16x16x32_f16 v[48:51], v[188:191], v[148:151], v[48:51]
	v_mfma_f32_16x16x32_f16 v[36:39], v[180:183], v[156:159], v[36:39]
	v_mfma_f32_16x16x32_f16 v[32:35], v[188:191], v[156:159], v[32:35]
	v_mfma_f32_16x16x32_f16 v[20:23], v[180:183], v[164:167], v[20:23]
	v_mfma_f32_16x16x32_f16 v[16:19], v[188:191], v[164:167], v[16:19]
	v_mfma_f32_16x16x32_f16 v[4:7], v[180:183], v[172:175], v[4:7]
	v_mfma_f32_16x16x32_f16 v[0:3], v[188:191], v[172:175], v[0:3]
	s_add_u32 s0, s0, 0x100
	s_addc_u32 s1, s1, 0
	s_add_u32 s27, s27, 0x100
	s_addc_u32 s33, s33, 0
	s_cmp_ge_u32 s38, s64
	s_mov_b32 s34, s38
	s_barrier
	s_cbranch_scc0 .LBB0_762
	s_setprio 0
	s_lshl_b32 s0, s84, 8
	s_or_b32 s27, s0, s65
	v_lshl_add_u32 v240, s30, 8, v200
	v_or_b32_e32 v216, s27, v202
	s_cmp_eq_u32 s93, 3
	s_cbranch_scc1 .Lst16_fast
	s_cmp_eq_u32 s93, 1
	s_cbranch_scc0 .Llora_no
	s_lshr_b32 s0, s84, 2
	s_cmp_lt_u32 s0, 2
	s_cbranch_scc1 .Llora_fast
